# attention: per-cluster s_setprio flips replaced by one static priority raise for waves 4-7
# baseline (speedup 1.0000x reference)
; DEV int vbsel() { return __builtin_amdgcn_readfirstlane((int)(threadIdx.x >> 8)); }
; #define ALOAD(kt) { const int key0_ = (kt) * 128; \
;     if (kc < 12) { _Pragma("unroll") for (int i = 0; i < 4; ++i) kr[i] = *(const u32x4*)(Kb + (size_t)(key0_ + krow + 32 * i) * 96 + kc * 8); } \
;     _Pragma("unroll") for (int i = 0; i < 2; ++i) vr[i] = *(const u32x4*)(Vt + (size_t)vrow * NKEY + key0_ + i * 64 + vc * 8); }
; #define ASTORE(slot) { char* sk_ = smem + (slot) * KB; char* sv_ = smem + (slot) * VB; \
;     if (kc < 12) { _Pragma("unroll") for (int i = 0; i < 4; ++i) *(u32x4*)(sk_ + kwo + i * 8192) = kr[i]; } \
;     _Pragma("unroll") for (int i = 0; i < 2; ++i) *(u32x4*)(sv_ + vwo + i * VB) = vr[i]; }
; #define ABAR() { asm volatile("s_waitcnt lgkmcnt(0)" ::: "memory"); __builtin_amdgcn_s_barrier(); asm volatile("" ::: "memory"); }
; DEV void attn_item(const P& p, int bh, int qrow0, int nkt, int outrow0, char* smem) {
;     ...
;   f32x4 o[4][2];
; #pragma unroll
;   for (int vt = 0; vt < 4; ++vt)
; #pragma unroll
;     for (int qt = 0; qt < 2; ++qt) o[vt][qt] = (f32x4){0.f, 0.f, 0.f, 0.f};
;   float mused[2] = {0.f, 0.f};
;   f32x4 osum[2] = {(f32x4){0.f, 0.f, 0.f, 0.f}, (f32x4){0.f, 0.f, 0.f, 0.f}};
;   const bf16x8 ones = __builtin_bit_cast(bf16x8, (u32x4){0x3f803f80u, 0x3f803f80u, 0x3f803f80u, 0x3f803f80u});
;   u32x4 kr[4], vr[2];
;   const int krow = tid >> 4, kc = tid & 15;
;   const int vrow = tid >> 3, vc = tid & 7;
;   const int kwo = vo + krow * 256 + ((kc ^ (krow & 15)) << 4), vwo = vo + VBASE + vrow * 128 + ((vc ^ ((vrow >> 1) & 7)) << 4);
;   const int kro = vo + l15 * 256, vro = vo + VBASE + l15 * 128;
;   f32x4 st[4][2];
;   bf16x8 pf[2][2], vf[2][4];
;     ...
;   const bool skew = vbsel() != 0;
;   asm volatile("" : "+s"(nkt));
;     ...
;   const int npair = nkt >> 1;
;   ALOAD(0); ASTORE(0); if (npair > 1) ALOAD(1); ABAR();
.LBB0_158:
	s_waitcnt lgkmcnt(0)
	s_barrier
	s_cmpk_gt_u32 s6, 0xff
	v_lshrrev_b32_e32 v1, 1, v207
	v_lshl_add_u32 v210, v207, 7, v4
	s_cselect_b64 s[4:5], -1, 0
	s_cmp_lt_i32 s23, 1
	v_xor_b32_e32 v211, v206, v1
	v_bitop3_b32 v208, v206, v1, 4 bitop3:0x36
	s_cbranch_scc1 .LBB0_214
	v_mov_b32_e32 v1, v41
	v_lshl_add_u64 v[204:205], s[2:3], 0, v[0:1]
	v_xor_b32_e32 v0, v206, v207
	v_lshlrev_b32_e32 v217, 4, v0
	v_bitop3_b32 v0, v206, v207, 4 bitop3:0x36
	v_mov_b32_e32 v42, v41
	v_mov_b32_e32 v43, v41
	v_lshlrev_b32_e32 v218, 4, v0
	v_bitop3_b32 v0, v206, v207, 8 bitop3:0x36
	v_mov_b32_e32 v40, v41
	v_mov_b32_e32 v221, 0
	v_mov_b64_e32 v[94:95], v[42:43]
	v_mov_b64_e32 v[98:99], v[42:43]
	v_mov_b64_e32 v[102:103], v[42:43]
	v_mov_b64_e32 v[106:107], v[42:43]
	v_mov_b64_e32 v[110:111], v[42:43]
	v_mov_b64_e32 v[114:115], v[42:43]
	v_mov_b64_e32 v[118:119], v[42:43]
	v_mov_b64_e32 v[122:123], v[42:43]
	v_lshl_add_u32 v214, v207, 8, v2
	v_lshlrev_b32_e32 v215, 4, v211
	v_lshlrev_b32_e32 v216, 4, v208
	v_lshlrev_b32_e32 v219, 4, v0
	s_mov_b32 s25, 0
	v_mov_b32_e32 v220, 0
	v_mov_b64_e32 v[92:93], v[40:41]
	v_mov_b64_e32 v[96:97], v[40:41]
	v_mov_b64_e32 v[100:101], v[40:41]
	v_mov_b64_e32 v[104:105], v[40:41]
	v_mov_b64_e32 v[108:109], v[40:41]
	v_mov_b64_e32 v[112:113], v[40:41]
	v_mov_b64_e32 v[116:117], v[40:41]
	v_mov_b64_e32 v[120:121], v[40:41]
	s_mov_b32 s10, 0
	s_mov_b32 s11, 0
	v_mov_b32_e32 v0, 0
	v_mov_b32_e32 v1, v221
	v_mov_b32_e32 v2, v221
	v_mov_b32_e32 v3, v221
	v_mov_b32_e32 v4, v221
	v_mov_b32_e32 v5, v221
	v_mov_b32_e32 v6, v221
	v_mov_b32_e32 v7, v221
	v_xor_b32_e32 v226, 0x80000000, v221
	v_xor_b32_e32 v230, 0x80000000, v220
	v_mov_b32_e32 v222, s56
	v_mov_b32_e32 v227, v226
	v_mov_b32_e32 v231, v230
	v_mov_b32_e32 v223, v222
	v_mov_b32_e32 v228, v226
	v_mov_b32_e32 v232, v230
	v_mov_b32_e32 v224, v222
	v_mov_b32_e32 v229, v226
	v_mov_b32_e32 v233, v230
	v_mov_b32_e32 v225, v222
	v_lshrrev_b32_e32 v8, 6, v201
	v_and_b32_e32 v9, 15, v237
	v_lshrrev_b32_e32 v10, 4, v237
	v_readfirstlane_b32 s2, v8
	s_lshl_b32 s40, s2, 12
	s_lshl_b32 s41, s2, 10
	v_lshl_add_u32 v11, v8, 4, v10
	v_add_u32_e32 v36, 0, v10
	v_xor_b32_e32 v36, v36, v9
	v_add_u32_e32 v37, 0, v11
	v_mul_u32_u24_e32 v37, 0xc0, v37
	v_lshl_add_u32 v13, v36, 4, v37
	v_add_u32_e32 v36, 4, v10
	v_xor_b32_e32 v36, v36, v9
	v_add_u32_e32 v37, 4, v11
	v_mul_u32_u24_e32 v37, 0xc0, v37
	v_lshl_add_u32 v14, v36, 4, v37
	v_add_u32_e32 v36, 8, v10
	v_xor_b32_e32 v36, v36, v9
	v_add_u32_e32 v37, 8, v11
	v_mul_u32_u24_e32 v37, 0xc0, v37
	v_lshl_add_u32 v15, v36, 4, v37
	v_add_u32_e32 v36, 12, v10
	v_xor_b32_e32 v36, v36, v9
	v_add_u32_e32 v37, 12, v11
	v_mul_u32_u24_e32 v37, 0xc0, v37
	v_lshl_add_u32 v12, v36, 4, v37
	v_lshrrev_b32_e32 v36, 3, v237
	v_lshl_add_u32 v36, v8, 3, v36
	v_bfe_u32 v37, v36, 1, 3
	v_and_b32_e32 v10, 7, v237
	v_xor_b32_e32 v37, v37, v10
	v_mul_u32_u24_e32 v36, 0x2200, v36
	v_lshl_add_u32 v234, v37, 4, v36
	s_mul_i32 s6, s19, 0xcc000
	s_mul_hi_i32 s7, s19, 0xcc000
	s_add_u32 s6, s14, s6
	s_addc_u32 s7, s15, s7
	s_add_u32 s6, s6, 0x6000
	s_addc_u32 s7, s7, 0
	s_mul_i32 s8, s19, 0x88000
	s_mul_hi_i32 s9, s19, 0x88000
	s_add_u32 s8, s16, s8
	s_addc_u32 s9, s17, s9
	s_add_u32 s8, s8, 0x100
	s_addc_u32 s9, s9, 0
	s_cmp_lt_i32 s23, 2
	s_cbranch_scc1 .Latt_loop
	s_mov_b32 s2, 2
	s_lshl_b32 s3, s2, 14
	s_add_i32 s3, s3, s40
	s_add_i32 m0, s3, 0x0
	s_nop 0
	global_load_lds_dwordx4 v13, s[6:7]
	s_add_i32 m0, s3, 0x400
	s_nop 0
	global_load_lds_dwordx4 v14, s[6:7]
	s_add_i32 m0, s3, 0x800
	s_nop 0
	global_load_lds_dwordx4 v15, s[6:7]
	s_add_i32 m0, s3, 0xc00
	s_nop 0
	global_load_lds_dwordx4 v12, s[6:7]
	s_lshl_b32 s3, s2, 13
	s_add_i32 s3, s3, s41
	s_add_i32 s3, s3, 0x18000
	v_add_u32_e32 v9, 0x80, v234
	s_mov_b32 m0, s3
	s_nop 0
	global_load_lds_dwordx4 v234, s[8:9]
	s_add_i32 m0, s3, 0x2000
	s_nop 0
	global_load_lds_dwordx4 v9, s[8:9]
	s_add_u32 s6, s6, 0x6000
	s_addc_u32 s7, s7, 0
	s_add_u32 s8, s8, 0x100
	s_addc_u32 s9, s9, 0
	s_and_b64 vcc, exec, s[4:5]
	s_cbranch_vccz .Latt_noprio
	s_setprio 1
; #define ALOAD(kt) { const int key0_ = (kt) * 128; \
;     if (kc < 12) { _Pragma("unroll") for (int i = 0; i < 4; ++i) kr[i] = *(const u32x4*)(Kb + (size_t)(key0_ + krow + 32 * i) * 96 + kc * 8); } \
;     _Pragma("unroll") for (int i = 0; i < 2; ++i) vr[i] = *(const u32x4*)(Vt + (size_t)vrow * NKEY + key0_ + i * 64 + vc * 8); }
; #define ASTORE(slot) { char* sk_ = smem + (slot) * KB; char* sv_ = smem + (slot) * VB; \
;     if (kc < 12) { _Pragma("unroll") for (int i = 0; i < 4; ++i) *(u32x4*)(sk_ + kwo + i * 8192) = kr[i]; } \
;     _Pragma("unroll") for (int i = 0; i < 2; ++i) *(u32x4*)(sv_ + vwo + i * VB) = vr[i]; }
; DEV void attn_item(const P& p, int bh, int qrow0, int nkt, int outrow0, char* smem) {
;     ...
;   for (int kp = 0; kp < npair; ++kp) {
;     const int sn = (s0 == 4) ? 0 : s0 + 2;
;     if (kp + 1 < npair) ASTORE(sn);
;     if (kp + 2 < npair) ALOAD(kp + 2);
.Latt_noprio:
.Latt_loop:
	s_add_i32 s2, s10, 2
	s_cmp_lg_u32 s10, 4
	s_cselect_b32 s24, s2, 0
	s_add_i32 s26, s11, 1
	v_lshl_add_u32 v8, s10, 14, v214
	v_add_u32_e32 v38, v8, v217
	v_add_u32_e32 v39, v8, v218
	v_add_u32_e32 v40, v8, v219
	s_lshl_b32 s27, s10, 13
	ds_read_b128 v[156:159], v38 offset:0
	ds_read_b128 v[160:163], v38 offset:4096
	ds_read_b128 v[164:167], v38 offset:8192
	ds_read_b128 v[168:171], v38 offset:12288
	ds_read_b128 v[172:175], v39 offset:0
	ds_read_b128 v[176:179], v39 offset:4096
	ds_read_b128 v[180:183], v39 offset:8192
	ds_read_b128 v[184:187], v39 offset:12288
	s_waitcnt lgkmcnt(7)
	v_mfma_f32_16x16x32_bf16 v[140:143], v[156:159], v[44:47], v[226:229]
	v_mfma_f32_16x16x32_bf16 v[124:127], v[156:159], v[56:59], v[230:233]
	s_waitcnt lgkmcnt(6)
	v_mfma_f32_16x16x32_bf16 v[144:147], v[160:163], v[44:47], v[226:229]
	v_mfma_f32_16x16x32_bf16 v[128:131], v[160:163], v[56:59], v[230:233]
	s_waitcnt lgkmcnt(5)
	v_mfma_f32_16x16x32_bf16 v[148:151], v[164:167], v[44:47], v[226:229]
	v_mfma_f32_16x16x32_bf16 v[132:135], v[164:167], v[56:59], v[230:233]
	s_waitcnt lgkmcnt(4)
	v_mfma_f32_16x16x32_bf16 v[152:155], v[168:171], v[44:47], v[226:229]
	v_mfma_f32_16x16x32_bf16 v[136:139], v[168:171], v[56:59], v[230:233]
	s_waitcnt lgkmcnt(3)
	v_mfma_f32_16x16x32_bf16 v[140:143], v[172:175], v[48:51], v[140:143]
	v_mfma_f32_16x16x32_bf16 v[124:127], v[172:175], v[60:63], v[124:127]
	ds_read_b128 v[156:159], v40 offset:0
	ds_read_b128 v[160:163], v40 offset:4096
	ds_read_b128 v[164:167], v40 offset:8192
	ds_read_b128 v[168:171], v40 offset:12288
	s_waitcnt lgkmcnt(6)
	v_mfma_f32_16x16x32_bf16 v[144:147], v[176:179], v[48:51], v[144:147]
	v_mfma_f32_16x16x32_bf16 v[128:131], v[176:179], v[60:63], v[128:131]
	s_waitcnt lgkmcnt(5)
	v_mfma_f32_16x16x32_bf16 v[148:151], v[180:183], v[48:51], v[148:151]
	v_mfma_f32_16x16x32_bf16 v[132:135], v[180:183], v[60:63], v[132:135]
	s_waitcnt lgkmcnt(4)
	v_mfma_f32_16x16x32_bf16 v[152:155], v[184:187], v[48:51], v[152:155]
	v_mfma_f32_16x16x32_bf16 v[136:139], v[184:187], v[60:63], v[136:139]
	s_waitcnt lgkmcnt(3)
	v_mfma_f32_16x16x32_bf16 v[140:143], v[156:159], v[52:55], v[140:143]
	v_mfma_f32_16x16x32_bf16 v[124:127], v[156:159], v[64:67], v[124:127]
	s_waitcnt lgkmcnt(2)
	v_mfma_f32_16x16x32_bf16 v[144:147], v[160:163], v[52:55], v[144:147]
	v_mfma_f32_16x16x32_bf16 v[128:131], v[160:163], v[64:67], v[128:131]
	s_waitcnt lgkmcnt(1)
	v_mfma_f32_16x16x32_bf16 v[148:151], v[164:167], v[52:55], v[148:151]
	v_mfma_f32_16x16x32_bf16 v[132:135], v[164:167], v[64:67], v[132:135]
	s_waitcnt lgkmcnt(0)
	v_mfma_f32_16x16x32_bf16 v[152:155], v[168:171], v[52:55], v[152:155]
	v_mfma_f32_16x16x32_bf16 v[136:139], v[168:171], v[64:67], v[136:139]
	s_add_i32 s2, s11, 2
	s_cmp_ge_i32 s2, s23
	s_cbranch_scc1 .Latt_nodma
	s_add_i32 s2, s24, 2
	s_cmp_lg_u32 s24, 4
	s_cselect_b32 s2, s2, 0
	s_lshl_b32 s3, s2, 14
	s_add_i32 s3, s3, s40
	s_add_i32 m0, s3, 0x0
	s_nop 0
	global_load_lds_dwordx4 v13, s[6:7]
	s_add_i32 m0, s3, 0x400
	s_nop 0
	global_load_lds_dwordx4 v14, s[6:7]
	s_add_i32 m0, s3, 0x800
	s_nop 0
	global_load_lds_dwordx4 v15, s[6:7]
	s_add_i32 m0, s3, 0xc00
	s_nop 0
	global_load_lds_dwordx4 v12, s[6:7]
	s_lshl_b32 s3, s2, 13
	s_add_i32 s3, s3, s41
	s_add_i32 s3, s3, 0x18000
	v_add_u32_e32 v9, 0x80, v234
	s_mov_b32 m0, s3
	s_nop 0
	global_load_lds_dwordx4 v234, s[8:9]
	s_add_i32 m0, s3, 0x2000
	s_nop 0
	global_load_lds_dwordx4 v9, s[8:9]
	s_add_u32 s6, s6, 0x6000
	s_addc_u32 s7, s7, 0
	s_add_u32 s8, s8, 0x100
	s_addc_u32 s9, s9, 0

.Latt_c_a:
	v_exp_f32_e32 v140, v140
	v_exp_f32_e32 v141, v141
	v_exp_f32_e32 v142, v142
	v_exp_f32_e32 v143, v143
	v_exp_f32_e32 v144, v144
	v_exp_f32_e32 v145, v145
	v_exp_f32_e32 v146, v146
	v_exp_f32_e32 v147, v147
	v_exp_f32_e32 v124, v124
	v_exp_f32_e32 v125, v125
	v_exp_f32_e32 v126, v126
	v_exp_f32_e32 v127, v127
	v_exp_f32_e32 v128, v128
	v_exp_f32_e32 v129, v129
	v_exp_f32_e32 v130, v130
	v_exp_f32_e32 v131, v131
	v_cvt_pk_bf16_f32 v140, v140, v141
	v_cvt_pk_bf16_f32 v141, v142, v143
	v_cvt_pk_bf16_f32 v142, v144, v145
	v_cvt_pk_bf16_f32 v143, v146, v147
	v_cvt_pk_bf16_f32 v124, v124, v125
	v_cvt_pk_bf16_f32 v125, v126, v127
	v_cvt_pk_bf16_f32 v126, v128, v129
	v_cvt_pk_bf16_f32 v127, v130, v131
	s_waitcnt lgkmcnt(4)
	ds_read_b128 v[156:159], v38 offset:16384
	ds_read_b128 v[160:163], v38 offset:20480
	ds_read_b128 v[164:167], v38 offset:24576
	ds_read_b128 v[168:171], v38 offset:28672
	ds_read_b128 v[172:175], v39 offset:16384
	ds_read_b128 v[176:179], v39 offset:20480
	ds_read_b128 v[180:183], v39 offset:24576
	ds_read_b128 v[184:187], v39 offset:28672
	s_waitcnt lgkmcnt(12)
	v_mfma_f32_16x16x32_bf16 v[92:95], v[16:19], v[140:143], v[92:95]
	v_exp_f32_e32 v148, v148
	v_exp_f32_e32 v149, v149
	v_mfma_f32_16x16x32_bf16 v[96:99], v[16:19], v[124:127], v[96:99]
	v_exp_f32_e32 v150, v150
	v_exp_f32_e32 v151, v151
	v_mfma_f32_16x16x32_bf16 v[100:103], v[20:23], v[140:143], v[100:103]
	v_exp_f32_e32 v152, v152
	v_exp_f32_e32 v153, v153
	v_mfma_f32_16x16x32_bf16 v[104:107], v[20:23], v[124:127], v[104:107]
	v_exp_f32_e32 v154, v154
	v_exp_f32_e32 v155, v155
	v_mfma_f32_16x16x32_bf16 v[108:111], v[24:27], v[140:143], v[108:111]
	v_cvt_pk_bf16_f32 v148, v148, v149
	v_cvt_pk_bf16_f32 v149, v150, v151
	v_mfma_f32_16x16x32_bf16 v[112:115], v[24:27], v[124:127], v[112:115]
	v_cvt_pk_bf16_f32 v150, v152, v153
	v_cvt_pk_bf16_f32 v151, v154, v155
	v_mfma_f32_16x16x32_bf16 v[116:119], v[28:31], v[140:143], v[116:119]
	v_exp_f32_e32 v132, v132
	v_exp_f32_e32 v133, v133
	v_mfma_f32_16x16x32_bf16 v[120:123], v[28:31], v[124:127], v[120:123]
	v_exp_f32_e32 v134, v134
	v_exp_f32_e32 v135, v135
	v_mfma_f32_16x16x32_bf16 v[0:3], v[222:225], v[140:143], v[0:3]
	v_exp_f32_e32 v136, v136
	v_exp_f32_e32 v137, v137
	v_mfma_f32_16x16x32_bf16 v[4:7], v[222:225], v[124:127], v[4:7]
	v_exp_f32_e32 v138, v138
	v_exp_f32_e32 v139, v139
	s_waitcnt lgkmcnt(8)
	v_mfma_f32_16x16x32_bf16 v[92:95], v[188:191], v[148:151], v[92:95]
	v_cvt_pk_bf16_f32 v132, v132, v133
	v_cvt_pk_bf16_f32 v133, v134, v135
	v_mfma_f32_16x16x32_bf16 v[100:103], v[192:195], v[148:151], v[100:103]
	v_cvt_pk_bf16_f32 v134, v136, v137
	v_cvt_pk_bf16_f32 v135, v138, v139
	v_mfma_f32_16x16x32_bf16 v[108:111], v[196:199], v[148:151], v[108:111]
	v_mfma_f32_16x16x32_bf16 v[116:119], v[32:35], v[148:151], v[116:119]
	v_mfma_f32_16x16x32_bf16 v[0:3], v[222:225], v[148:151], v[0:3]
	v_mfma_f32_16x16x32_bf16 v[96:99], v[188:191], v[132:135], v[96:99]
	v_mfma_f32_16x16x32_bf16 v[104:107], v[192:195], v[132:135], v[104:107]
	v_mfma_f32_16x16x32_bf16 v[112:115], v[196:199], v[132:135], v[112:115]
	v_mfma_f32_16x16x32_bf16 v[120:123], v[32:35], v[132:135], v[120:123]
	v_mfma_f32_16x16x32_bf16 v[4:7], v[222:225], v[132:135], v[4:7]
	s_waitcnt lgkmcnt(7)
	v_mfma_f32_16x16x32_bf16 v[140:143], v[156:159], v[44:47], v[226:229]
	v_mfma_f32_16x16x32_bf16 v[124:127], v[156:159], v[56:59], v[230:233]
	s_waitcnt lgkmcnt(6)
	v_mfma_f32_16x16x32_bf16 v[144:147], v[160:163], v[44:47], v[226:229]
	v_mfma_f32_16x16x32_bf16 v[128:131], v[160:163], v[56:59], v[230:233]
	s_waitcnt lgkmcnt(5)
	v_mfma_f32_16x16x32_bf16 v[148:151], v[164:167], v[44:47], v[226:229]
	v_mfma_f32_16x16x32_bf16 v[132:135], v[164:167], v[56:59], v[230:233]
	s_waitcnt lgkmcnt(4)
	v_mfma_f32_16x16x32_bf16 v[152:155], v[168:171], v[44:47], v[226:229]
	v_mfma_f32_16x16x32_bf16 v[136:139], v[168:171], v[56:59], v[230:233]
	s_waitcnt lgkmcnt(3)
	v_mfma_f32_16x16x32_bf16 v[140:143], v[172:175], v[48:51], v[140:143]
	v_mfma_f32_16x16x32_bf16 v[124:127], v[172:175], v[60:63], v[124:127]
	ds_read_b128 v[156:159], v40 offset:16384
	ds_read_b128 v[160:163], v40 offset:20480
	ds_read_b128 v[164:167], v40 offset:24576
	ds_read_b128 v[168:171], v40 offset:28672
	s_waitcnt lgkmcnt(6)
	v_mfma_f32_16x16x32_bf16 v[144:147], v[176:179], v[48:51], v[144:147]
	v_mfma_f32_16x16x32_bf16 v[128:131], v[176:179], v[60:63], v[128:131]
	s_waitcnt lgkmcnt(5)
	v_mfma_f32_16x16x32_bf16 v[148:151], v[180:183], v[48:51], v[148:151]
	v_mfma_f32_16x16x32_bf16 v[132:135], v[180:183], v[60:63], v[132:135]
	s_waitcnt lgkmcnt(4)
	v_mfma_f32_16x16x32_bf16 v[152:155], v[184:187], v[48:51], v[152:155]
	v_mfma_f32_16x16x32_bf16 v[136:139], v[184:187], v[60:63], v[136:139]
	s_waitcnt lgkmcnt(3)
	v_mfma_f32_16x16x32_bf16 v[140:143], v[156:159], v[52:55], v[140:143]
	v_mfma_f32_16x16x32_bf16 v[124:127], v[156:159], v[64:67], v[124:127]
	s_waitcnt lgkmcnt(2)
	v_mfma_f32_16x16x32_bf16 v[144:147], v[160:163], v[52:55], v[144:147]
	v_mfma_f32_16x16x32_bf16 v[128:131], v[160:163], v[64:67], v[128:131]
	s_waitcnt lgkmcnt(1)
	v_mfma_f32_16x16x32_bf16 v[148:151], v[164:167], v[52:55], v[148:151]
	v_mfma_f32_16x16x32_bf16 v[132:135], v[164:167], v[64:67], v[132:135]
	s_waitcnt lgkmcnt(0)
	v_mfma_f32_16x16x32_bf16 v[152:155], v[168:171], v[52:55], v[152:155]
	v_mfma_f32_16x16x32_bf16 v[136:139], v[168:171], v[64:67], v[136:139]
	v_max3_f32 v36, v140, v141, v142
	v_max3_f32 v37, v124, v125, v126
	v_max3_f32 v36, v36, v143, v144
	v_max3_f32 v37, v37, v127, v128
	v_max3_f32 v36, v36, v145, v146
	v_max3_f32 v37, v37, v129, v130
	v_max3_f32 v36, v36, v147, v148
	v_max3_f32 v37, v37, v131, v132
	v_max3_f32 v36, v36, v149, v150
	v_max3_f32 v37, v37, v133, v134
	v_max3_f32 v36, v36, v151, v152
	v_max3_f32 v37, v37, v135, v136
	v_max3_f32 v36, v36, v153, v154
	v_max3_f32 v37, v37, v137, v138
	v_max3_f32 v36, v36, v155, v155
	v_max3_f32 v37, v37, v139, v139
	v_max_f32_e32 v9, v36, v37
	v_cmp_lt_f32_e32 vcc, s44, v9
	ds_read_b128 v[16:19], v42 offset:8192
	ds_read_b128 v[20:23], v42 offset:10240
	ds_read_b128 v[24:27], v42 offset:12288
	ds_read_b128 v[28:31], v42 offset:14336
	ds_read_b128 v[188:191], v43 offset:8192
	ds_read_b128 v[192:195], v43 offset:10240
	ds_read_b128 v[196:199], v43 offset:12288
	ds_read_b128 v[32:35], v43 offset:14336
	s_cbranch_vccnz .Latt_rare_b
.Latt_c_b:
	v_exp_f32_e32 v140, v140
	v_exp_f32_e32 v141, v141
	v_exp_f32_e32 v142, v142
	v_exp_f32_e32 v143, v143
	v_exp_f32_e32 v144, v144
	v_exp_f32_e32 v145, v145
	v_exp_f32_e32 v146, v146
	v_exp_f32_e32 v147, v147
	v_exp_f32_e32 v124, v124
	v_exp_f32_e32 v125, v125
	v_exp_f32_e32 v126, v126
	v_exp_f32_e32 v127, v127
	v_exp_f32_e32 v128, v128
	v_exp_f32_e32 v129, v129
	v_exp_f32_e32 v130, v130
	v_exp_f32_e32 v131, v131
	v_cvt_pk_bf16_f32 v140, v140, v141
	v_cvt_pk_bf16_f32 v141, v142, v143
	v_cvt_pk_bf16_f32 v142, v144, v145
	v_cvt_pk_bf16_f32 v143, v146, v147
	v_cvt_pk_bf16_f32 v124, v124, v125
	v_cvt_pk_bf16_f32 v125, v126, v127
	v_cvt_pk_bf16_f32 v126, v128, v129
	v_cvt_pk_bf16_f32 v127, v130, v131
	s_waitcnt lgkmcnt(4)
	v_mfma_f32_16x16x32_bf16 v[92:95], v[16:19], v[140:143], v[92:95]
	v_exp_f32_e32 v148, v148
	v_exp_f32_e32 v149, v149
	v_mfma_f32_16x16x32_bf16 v[96:99], v[16:19], v[124:127], v[96:99]
	v_exp_f32_e32 v150, v150
	v_exp_f32_e32 v151, v151
	v_mfma_f32_16x16x32_bf16 v[100:103], v[20:23], v[140:143], v[100:103]
	v_exp_f32_e32 v152, v152
	v_exp_f32_e32 v153, v153
	v_mfma_f32_16x16x32_bf16 v[104:107], v[20:23], v[124:127], v[104:107]
	v_exp_f32_e32 v154, v154
	v_exp_f32_e32 v155, v155
	v_mfma_f32_16x16x32_bf16 v[108:111], v[24:27], v[140:143], v[108:111]
	v_cvt_pk_bf16_f32 v148, v148, v149
	v_cvt_pk_bf16_f32 v149, v150, v151
	v_mfma_f32_16x16x32_bf16 v[112:115], v[24:27], v[124:127], v[112:115]
	v_cvt_pk_bf16_f32 v150, v152, v153
	v_cvt_pk_bf16_f32 v151, v154, v155
	v_mfma_f32_16x16x32_bf16 v[116:119], v[28:31], v[140:143], v[116:119]
	v_exp_f32_e32 v132, v132
	v_exp_f32_e32 v133, v133
	v_mfma_f32_16x16x32_bf16 v[120:123], v[28:31], v[124:127], v[120:123]
	v_exp_f32_e32 v134, v134
	v_exp_f32_e32 v135, v135
	v_mfma_f32_16x16x32_bf16 v[0:3], v[222:225], v[140:143], v[0:3]
	v_exp_f32_e32 v136, v136
	v_exp_f32_e32 v137, v137
	v_mfma_f32_16x16x32_bf16 v[4:7], v[222:225], v[124:127], v[4:7]
	v_exp_f32_e32 v138, v138
	v_exp_f32_e32 v139, v139
	s_waitcnt lgkmcnt(0)
	v_mfma_f32_16x16x32_bf16 v[92:95], v[188:191], v[148:151], v[92:95]
	v_cvt_pk_bf16_f32 v132, v132, v133
	v_cvt_pk_bf16_f32 v133, v134, v135
	v_mfma_f32_16x16x32_bf16 v[100:103], v[192:195], v[148:151], v[100:103]
	v_cvt_pk_bf16_f32 v134, v136, v137
	v_cvt_pk_bf16_f32 v135, v138, v139
	v_mfma_f32_16x16x32_bf16 v[108:111], v[196:199], v[148:151], v[108:111]
	v_mfma_f32_16x16x32_bf16 v[116:119], v[32:35], v[148:151], v[116:119]
	v_mfma_f32_16x16x32_bf16 v[0:3], v[222:225], v[148:151], v[0:3]
	v_mfma_f32_16x16x32_bf16 v[96:99], v[188:191], v[132:135], v[96:99]
	v_mfma_f32_16x16x32_bf16 v[104:107], v[192:195], v[132:135], v[104:107]
	v_mfma_f32_16x16x32_bf16 v[112:115], v[196:199], v[132:135], v[112:115]
	v_mfma_f32_16x16x32_bf16 v[120:123], v[32:35], v[132:135], v[120:123]
	v_mfma_f32_16x16x32_bf16 v[4:7], v[222:225], v[132:135], v[4:7]
	s_add_i32 s2, s11, 2
	s_cmp_ge_i32 s2, s23
	s_cbranch_scc1 .Latt_w0
	s_waitcnt vmcnt(6)
	s_branch .Latt_wd

; DEV unsigned pk_bf16(float lo, float hi) { unsigned r; asm("v_cvt_pk_bf16_f32 %0, %1, %2" : "=v"(r) : "v"(lo), "v"(hi)); return r; }
; DEV void attn_item(const P& p, int bh, int qrow0, int nkt, int outrow0, char* smem) {
;     ...
;   const int h = bh & 7;
; #pragma unroll
;   for (int qt = 0; qt < 2; ++qt) {
;     const float inv = 1.0f / osum[qt][0];
;     const int row = outrow0 + wid * 32 + qt * 16 + l15;
; #pragma unroll
;     for (int vt = 0; vt < 4; ++vt) {
;       const f32x4 v = o[vt][qt] * inv;
;       *(u32x2*)(Z + (size_t)row * LDZ + ZAO + h * 64 + vt * 16 + lq * 4) = (u32x2){pk_bf16(v[0], v[1]), pk_bf16(v[2], v[3])};
;     }
;   }
.Latt_exit:
	s_setprio 0
	s_nop 7
	v_mov_b64_e32 v[176:177], v[92:93]
	v_mov_b64_e32 v[178:179], v[94:95]
	v_mov_b64_e32 v[172:173], v[100:101]
	v_mov_b64_e32 v[174:175], v[102:103]
	v_mov_b64_e32 v[168:169], v[108:109]
	v_mov_b64_e32 v[170:171], v[110:111]
	v_mov_b64_e32 v[164:165], v[116:117]
	v_mov_b64_e32 v[166:167], v[118:119]
	v_mov_b64_e32 v[160:161], v[96:97]
	v_mov_b64_e32 v[162:163], v[98:99]
	v_mov_b64_e32 v[156:157], v[104:105]
	v_mov_b64_e32 v[158:159], v[106:107]
	v_mov_b64_e32 v[36:37], v[112:113]
	v_mov_b64_e32 v[38:39], v[114:115]
	v_mov_b64_e32 v[32:33], v[120:121]
	v_mov_b64_e32 v[34:35], v[122:123]
	v_mov_b64_e32 v[22:23], v[4:5]
	v_mov_b64_e32 v[24:25], v[6:7]
	s_branch .LBB0_149
